# post_a sample rows (S5 readout): the 66 loads of a 64-column step renamed into a 27-quad ring and streamed (was 5 batch-wait round trips per step, 40 per row)
# baseline (speedup 1.0000x reference)
.LBB0_1529:
	v_lshl_add_u64 v[68:69], s[6:7], 0, v[56:57]
	s_mov_b64 s[100:101], 0x422e2000
	v_lshl_add_u64 v[100:101], v[68:69], 0, s[100:101]
	global_load_dwordx4 v[108:111], v[100:101], off offset:48
	global_load_dwordx4 v[112:115], v[100:101], off offset:32
	global_load_dwordx4 v[116:119], v[100:101], off offset:16
	s_mov_b64 s[100:101], 0x46762000
	v_lshl_add_u64 v[100:101], v[68:69], 0, s[100:101]
	global_load_dwordx4 v[124:127], v[100:101], off offset:48
	global_load_dwordx4 v[128:131], v[100:101], off offset:32
	global_load_dwordx4 v[132:135], v[100:101], off offset:16
	s_mov_b64 s[100:101], 0x422e2040
	v_lshl_add_u64 v[100:101], v[68:69], 0, s[100:101]
	global_load_dwordx4 v[172:175], v[100:101], off offset:48
	global_load_dwordx4 v[176:179], v[100:101], off offset:32
	global_load_dwordx4 v[180:183], v[100:101], off offset:16
	s_mov_b64 s[100:101], 0x46762040
	v_lshl_add_u64 v[100:101], v[68:69], 0, s[100:101]
	global_load_dwordx4 v[188:191], v[100:101], off offset:48
	global_load_dwordx4 v[192:195], v[100:101], off offset:32
	global_load_dwordx4 v[196:199], v[100:101], off offset:16
	v_add_co_u32_e32 v72, vcc, 0x422e2000, v68
	s_mov_b64 s[16:17], 0x422e2000
	s_nop 0
	v_addc_co_u32_e32 v73, vcc, 0, v69, vcc
	global_load_dwordx4 v[104:107], v[72:73], off
	global_load_dwordx4 v[168:171], v[72:73], off offset:64
	s_mov_b32 s1, 0x46762000
	v_lshl_add_u64 v[12:13], v[68:69], 0, s[16:17]
	s_mov_b64 s[16:17], 0x46762000
	v_add_co_u32_e32 v70, vcc, s1, v68
	v_lshl_add_u64 v[28:29], v[68:69], 0, s[16:17]
	s_nop 0
	v_addc_co_u32_e32 v71, vcc, 0, v69, vcc
	global_load_dwordx4 v[120:123], v[70:71], off
	global_load_dwordx4 v[184:187], v[70:71], off offset:64
	v_lshl_add_u64 v[66:67], v[52:53], 0, s[14:15]
	global_load_dwordx4 v[136:139], v[66:67], off offset:48
	global_load_dwordx4 v[140:143], v[66:67], off offset:32
	global_load_dwordx4 v[144:147], v[66:67], off offset:16
	global_load_dwordx4 v[148:151], v[66:67], off
	global_load_dwordx4 v[200:203], v[66:67], off offset:112
	global_load_dwordx4 v[204:207], v[66:67], off offset:96
	global_load_dwordx4 v[208:211], v[66:67], off offset:80
	v_lshl_add_u64 v[64:65], v[54:55], 0, s[14:15]
	global_load_dwordx4 v[152:155], v[64:65], off offset:48
	global_load_dwordx4 v[156:159], v[64:65], off offset:32
	global_load_dwordx4 v[160:163], v[64:65], off offset:16
	global_load_dwordx4 v[164:167], v[64:65], off
	s_nop 0
	s_nop 0
	s_nop 0
	s_nop 0
	s_mov_b64 s[16:17], 0x422e2040
	s_waitcnt vmcnt(7)
	v_mul_f32_e32 v105, v105, v149
	v_fmac_f32_e32 v105, v104, v148
	v_fmac_f32_e32 v105, v106, v150
	v_fmac_f32_e32 v105, v107, v151
	s_mov_b64 s[100:101], 0x46762080
	v_lshl_add_u64 v[100:101], v[68:69], 0, s[100:101]
	global_load_dwordx4 v[148:151], v[100:101], off offset:48
	s_waitcnt vmcnt(1)
	v_mul_f32_e32 v0, v121, v165
	v_fmac_f32_e32 v0, v120, v164
	v_fmac_f32_e32 v0, v122, v166
	v_fmac_f32_e32 v0, v123, v167
	global_load_dwordx4 v[120:123], v[64:65], off offset:64
	global_load_dwordx4 v[164:167], v[66:67], off offset:128
	v_sub_f32_e32 v0, v105, v0
	global_load_dwordx4 v[104:107], v[66:67], off offset:64
	s_waitcnt vmcnt(12)
	v_mul_f32_e32 v1, v117, v145
	s_waitcnt vmcnt(5)
	v_mul_f32_e32 v2, v133, v161
	v_fmac_f32_e32 v1, v116, v144
	v_fmac_f32_e32 v2, v132, v160
	v_fmac_f32_e32 v1, v118, v146
	v_fmac_f32_e32 v2, v134, v162
	v_fmac_f32_e32 v1, v119, v147
	global_load_dwordx4 v[116:119], v[64:65], off offset:80
	global_load_dwordx4 v[144:147], v[100:101], off offset:32
	v_fmac_f32_e32 v2, v135, v163
	s_mov_b64 s[100:101], 0x422e2080
	v_lshl_add_u64 v[100:101], v[68:69], 0, s[100:101]
	global_load_dwordx4 v[132:135], v[100:101], off offset:48
	global_load_dwordx4 v[160:163], v[66:67], off offset:176
	v_add_f32_e32 v0, 0, v0
	v_sub_f32_e32 v1, v1, v2
	v_add_f32_e32 v0, v0, v1
	s_waitcnt vmcnt(17)
	v_mul_f32_e32 v1, v113, v141
	s_waitcnt vmcnt(10)
	v_mul_f32_e32 v2, v129, v157
	v_fmac_f32_e32 v1, v112, v140
	v_fmac_f32_e32 v2, v128, v156
	v_fmac_f32_e32 v1, v114, v142
	v_fmac_f32_e32 v2, v130, v158
	v_fmac_f32_e32 v1, v115, v143
	global_load_dwordx4 v[112:115], v[64:65], off offset:96
	global_load_dwordx4 v[140:143], v[70:71], off offset:128
	v_fmac_f32_e32 v2, v131, v159
	global_load_dwordx4 v[128:131], v[100:101], off offset:32
	global_load_dwordx4 v[156:159], v[66:67], off offset:160
	v_sub_f32_e32 v1, v1, v2
	v_add_f32_e32 v0, v0, v1
	s_waitcnt vmcnt(22)
	v_mul_f32_e32 v1, v109, v137
	s_waitcnt vmcnt(15)
	v_mul_f32_e32 v2, v125, v153
	v_fmac_f32_e32 v1, v108, v136
	v_fmac_f32_e32 v2, v124, v152
	v_fmac_f32_e32 v1, v110, v138
	v_fmac_f32_e32 v2, v126, v154
	v_fmac_f32_e32 v1, v111, v139
	global_load_dwordx4 v[108:111], v[64:65], off offset:112
	global_load_dwordx4 v[136:139], v[100:101], off offset:16
	v_fmac_f32_e32 v2, v127, v155
	global_load_dwordx4 v[124:127], v[72:73], off offset:128
	s_mov_b64 s[100:101], 0x46762080
	v_lshl_add_u64 v[100:101], v[68:69], 0, s[100:101]
	global_load_dwordx4 v[152:155], v[100:101], off offset:16
	v_lshl_add_u64 v[4:5], v[68:69], 0, s[16:17]
	s_mov_b64 s[16:17], 0x46762040
	v_sub_f32_e32 v1, v1, v2
	v_lshl_add_u64 v[8:9], v[68:69], 0, s[16:17]
	v_add_f32_e32 v94, v0, v1
	s_nop 0
	s_nop 0
	s_mov_b64 s[16:17], 0x422e2080
	s_waitcnt vmcnt(12)
	v_mul_f32_e32 v169, v169, v105
	v_fmac_f32_e32 v169, v168, v104
	s_waitcnt vmcnt(21)
	v_mul_f32_e32 v177, v177, v205
	s_waitcnt vmcnt(20)
	v_mul_f32_e32 v181, v181, v209
	s_waitcnt vmcnt(14)
	v_mul_f32_e32 v32, v185, v121
	v_fmac_f32_e32 v32, v184, v120
	v_fmac_f32_e32 v181, v180, v208
	s_waitcnt vmcnt(11)
	v_mul_f32_e32 v24, v197, v117
	v_fmac_f32_e32 v169, v170, v106
	v_fmac_f32_e32 v32, v186, v122
	v_fmac_f32_e32 v24, v196, v116
	v_fmac_f32_e32 v177, v176, v204
	s_waitcnt vmcnt(7)
	v_mul_f32_e32 v12, v193, v113
	s_waitcnt vmcnt(22)
	v_mul_f32_e32 v173, v173, v201
	v_fmac_f32_e32 v169, v171, v107
	s_mov_b64 s[100:101], 0x467620c0
	v_lshl_add_u64 v[100:101], v[68:69], 0, s[100:101]
	global_load_dwordx4 v[104:107], v[100:101], off offset:48
	v_fmac_f32_e32 v32, v187, v123
	global_load_dwordx4 v[184:187], v[64:65], off offset:144
	global_load_dwordx4 v[120:123], v[66:67], off offset:192
	v_fmac_f32_e32 v181, v182, v210
	v_fmac_f32_e32 v24, v198, v118
	v_fmac_f32_e32 v12, v192, v112
	v_fmac_f32_e32 v173, v172, v200
	s_waitcnt vmcnt(6)
	v_mul_f32_e32 v0, v189, v109
	v_sub_f32_e32 v32, v169, v32
	global_load_dwordx4 v[168:171], v[66:67], off offset:144
	v_fmac_f32_e32 v181, v183, v211
	global_load_dwordx4 v[208:211], v[100:101], off offset:32
	v_fmac_f32_e32 v24, v199, v119
	s_mov_b64 s[100:101], 0x422e20c0
	v_lshl_add_u64 v[100:101], v[68:69], 0, s[100:101]
	global_load_dwordx4 v[196:199], v[100:101], off offset:48
	global_load_dwordx4 v[116:119], v[66:67], off offset:240
	v_fmac_f32_e32 v177, v178, v206
	v_fmac_f32_e32 v12, v194, v114
	v_fmac_f32_e32 v0, v188, v108
	v_add_f32_e32 v32, v94, v32
	v_sub_f32_e32 v24, v181, v24
	global_load_dwordx4 v[180:183], v[64:65], off offset:128
	v_fmac_f32_e32 v177, v179, v207
	global_load_dwordx4 v[204:207], v[70:71], off offset:192
	v_fmac_f32_e32 v12, v195, v115
	global_load_dwordx4 v[192:195], v[100:101], off offset:32
	global_load_dwordx4 v[112:115], v[66:67], off offset:224
	v_fmac_f32_e32 v173, v174, v202
	v_fmac_f32_e32 v0, v190, v110
	v_add_f32_e32 v24, v32, v24
	v_sub_f32_e32 v12, v177, v12
	global_load_dwordx4 v[176:179], v[64:65], off offset:176
	v_fmac_f32_e32 v173, v175, v203
	global_load_dwordx4 v[200:203], v[100:101], off offset:16
	v_fmac_f32_e32 v0, v191, v111
	global_load_dwordx4 v[188:191], v[72:73], off offset:192
	s_mov_b64 s[100:101], 0x467620c0
	v_lshl_add_u64 v[100:101], v[68:69], 0, s[100:101]
	global_load_dwordx4 v[108:111], v[100:101], off offset:16
	v_add_f32_e32 v12, v24, v12
	v_sub_f32_e32 v0, v173, v0
	global_load_dwordx4 v[172:175], v[64:65], off offset:160
	v_add_f32_e32 v96, v12, v0
	v_lshl_add_u64 v[0:1], v[68:69], 0, s[16:17]
	s_mov_b64 s[16:17], 0x46762080
	v_lshl_add_u64 v[28:29], v[68:69], 0, s[16:17]
	s_nop 0
	s_nop 0
	s_mov_b64 s[16:17], 0x422e20c0
	s_waitcnt vmcnt(17)
	v_mov_b32_e32 v94, v124
	s_waitcnt vmcnt(29)
	v_mov_b32_e32 v98, v164
	s_waitcnt vmcnt(12)
	v_mov_b32_e32 v99, v168
	s_waitcnt vmcnt(18)
	v_mov_b32_e32 v95, v136
	v_mov_b32_e32 v20, v125
	v_mov_b32_e32 v74, v165
	v_mov_b32_e32 v21, v137
	v_mov_b32_e32 v75, v169
	v_pk_mul_f32 v[16:17], v[20:21], v[74:75]
	v_mov_b32_e32 v20, v126
	v_pk_fma_f32 v[16:17], v[94:95], v[98:99], v[16:17]
	v_mov_b32_e32 v21, v138
	v_mov_b32_e32 v164, v166
	v_mov_b32_e32 v41, v170
	v_mov_b32_e32 v40, v164
	v_pk_fma_f32 v[16:17], v[20:21], v[40:41], v[16:17]
	v_mov_b32_e32 v22, v127
	global_load_dwordx4 v[124:127], v[66:67], off offset:208
	v_mov_b32_e32 v76, v167
	s_waitcnt vmcnt(17)
	v_mov_b32_e32 v19, v152
	s_waitcnt vmcnt(15)
	v_mov_b32_e32 v21, v184
	s_waitcnt vmcnt(23)
	v_mov_b32_e32 v28, v141
	s_waitcnt vmcnt(9)
	v_mov_b32_e32 v90, v181
	v_mov_b32_e32 v23, v139
	v_mov_b32_e32 v77, v171
	v_pk_fma_f32 v[16:17], v[22:23], v[76:77], v[16:17]
	global_load_dwordx4 v[136:139], v[64:65], off offset:192
	v_mov_b32_e32 v18, v140
	v_mov_b32_e32 v20, v180
	v_mov_b32_e32 v29, v153
	v_mov_b32_e32 v91, v185
	v_pk_mul_f32 v[22:23], v[28:29], v[90:91]
	s_nop 0
	v_pk_fma_f32 v[18:19], v[18:19], v[20:21], v[22:23]
	v_mov_b32_e32 v20, v142
	v_mov_b32_e32 v21, v154
	v_mov_b32_e32 v22, v182
	v_mov_b32_e32 v23, v186
	v_pk_fma_f32 v[18:19], v[20:21], v[22:23], v[18:19]
	v_mov_b32_e32 v30, v143
	global_load_dwordx4 v[140:143], v[64:65], off offset:208
	v_mov_b32_e32 v92, v183
	v_mov_b32_e32 v31, v155
	v_mov_b32_e32 v93, v187
	v_pk_fma_f32 v[18:19], v[30:31], v[92:93], v[18:19]
	s_nop 0
	v_pk_add_f32 v[16:17], v[16:17], v[18:19] neg_lo:[0,1] neg_hi:[0,1]
	s_waitcnt vmcnt(27)
	v_mov_b32_e32 v19, v160
	v_add_f32_e32 v16, v96, v16
	v_add_f32_e32 v20, v16, v17
	s_waitcnt vmcnt(28)
	v_mov_b32_e32 v17, v132
	s_waitcnt vmcnt(24)
	v_mov_b32_e32 v8, v129
	s_waitcnt vmcnt(23)
	v_mov_b32_e32 v36, v157
	v_mov_b32_e32 v16, v128
	v_mov_b32_e32 v18, v156
	v_mov_b32_e32 v9, v133
	v_mov_b32_e32 v37, v161
	v_pk_mul_f32 v[8:9], v[8:9], v[36:37]
	v_mov_b32_e32 v128, v130
	v_pk_fma_f32 v[8:9], v[16:17], v[18:19], v[8:9]
	v_mov_b32_e32 v13, v134
	v_mov_b32_e32 v16, v158
	v_mov_b32_e32 v17, v162
	v_mov_b32_e32 v12, v128
	v_pk_fma_f32 v[8:9], v[12:13], v[16:17], v[8:9]
	v_mov_b32_e32 v10, v131
	global_load_dwordx4 v[128:131], v[64:65], off offset:224
	v_mov_b32_e32 v38, v159
	v_mov_b32_e32 v11, v135
	v_mov_b32_e32 v39, v163
	v_pk_fma_f32 v[8:9], v[10:11], v[38:39], v[8:9]
	s_waitcnt vmcnt(35)
	v_mov_b32_e32 v11, v148
	s_waitcnt vmcnt(8)
	v_mov_b32_e32 v13, v176
	s_waitcnt vmcnt(30)
	v_mov_b32_e32 v0, v145
	s_waitcnt vmcnt(4)
	v_mov_b32_e32 v82, v173
	v_mov_b32_e32 v10, v144
	v_mov_b32_e32 v12, v172
	v_mov_b32_e32 v1, v149
	v_mov_b32_e32 v83, v177
	v_pk_mul_f32 v[0:1], v[0:1], v[82:83]
	v_mov_b32_e32 v144, v146
	v_pk_fma_f32 v[0:1], v[10:11], v[12:13], v[0:1]
	v_mov_b32_e32 v5, v150
	v_mov_b32_e32 v10, v174
	v_mov_b32_e32 v11, v178
	v_mov_b32_e32 v4, v144
	v_pk_fma_f32 v[0:1], v[4:5], v[10:11], v[0:1]
	v_mov_b32_e32 v2, v147
	global_load_dword v144, v[62:63], off
	v_mov_b32_e32 v84, v175
	v_mov_b32_e32 v3, v151
	v_mov_b32_e32 v85, v179
	v_pk_fma_f32 v[0:1], v[2:3], v[84:85], v[0:1]
	s_nop 0
	v_pk_add_f32 v[0:1], v[8:9], v[0:1] neg_lo:[0,1] neg_hi:[0,1]
	global_load_dwordx4 v[132:135], v[64:65], off offset:240
	s_nop 0
	v_add_f32_e32 v0, v20, v0
	v_add_f32_e32 v2, v0, v1
	v_lshl_add_u64 v[0:1], v[68:69], 0, s[16:17]
	s_mov_b64 s[16:17], 0x467620c0
	v_lshl_add_u64 v[0:1], v[68:69], 0, s[16:17]
	s_nop 0
	s_waitcnt vmcnt(8)
	v_mov_b32_e32 v0, v188
	s_waitcnt vmcnt(19)
	v_mov_b32_e32 v88, v120
	s_waitcnt vmcnt(5)
	v_mov_b32_e32 v89, v124
	s_waitcnt vmcnt(9)
	v_mov_b32_e32 v1, v200
	v_mov_b32_e32 v16, v189
	v_mov_b32_e32 v72, v121
	v_mov_b32_e32 v17, v201
	v_mov_b32_e32 v73, v125
	v_pk_mul_f32 v[4:5], v[16:17], v[72:73]
	v_mov_b32_e32 v16, v122
	v_pk_fma_f32 v[0:1], v[0:1], v[88:89], v[4:5]
	v_mov_b32_e32 v4, v190
	v_mov_b32_e32 v5, v202
	v_mov_b32_e32 v17, v126
	v_pk_fma_f32 v[0:1], v[4:5], v[16:17], v[0:1]
	v_mov_b32_e32 v18, v191
	s_waitcnt vmcnt(7)
	v_mov_b32_e32 v5, v108
	s_waitcnt vmcnt(3)
	v_mov_b32_e32 v7, v140
	s_waitcnt vmcnt(13)
	v_mov_b32_e32 v32, v205
	s_waitcnt vmcnt(4)
	v_mov_b32_e32 v64, v137
	v_mov_b32_e32 v4, v204
	v_mov_b32_e32 v6, v136
	v_mov_b32_e32 v33, v109
	v_mov_b32_e32 v65, v141
	v_pk_mul_f32 v[16:17], v[32:33], v[64:65]
	v_mov_b32_e32 v74, v123
	v_pk_fma_f32 v[4:5], v[4:5], v[6:7], v[16:17]
	v_mov_b32_e32 v6, v206
	v_mov_b32_e32 v7, v110
	v_mov_b32_e32 v16, v138
	v_mov_b32_e32 v17, v142
	v_pk_fma_f32 v[4:5], v[6:7], v[16:17], v[4:5]
	v_mov_b32_e32 v34, v207
	v_mov_b32_e32 v66, v139
	v_mov_b32_e32 v19, v203
	v_mov_b32_e32 v75, v127
	v_pk_fma_f32 v[0:1], v[18:19], v[74:75], v[0:1]
	v_mov_b32_e32 v35, v111
	v_mov_b32_e32 v67, v143
	v_pk_fma_f32 v[4:5], v[34:35], v[66:67], v[4:5]
	s_waitcnt vmcnt(15)
	v_mov_b32_e32 v3, v116
	v_pk_add_f32 v[0:1], v[0:1], v[4:5] neg_lo:[0,1] neg_hi:[0,1]
	s_waitcnt vmcnt(11)
	v_mov_b32_e32 v40, v113
	v_add_f32_e32 v0, v2, v0
	v_add_f32_e32 v16, v0, v1
	s_waitcnt vmcnt(16)
	v_mov_b32_e32 v1, v196
	s_waitcnt vmcnt(12)
	v_mov_b32_e32 v12, v193
	v_mov_b32_e32 v0, v192
	v_mov_b32_e32 v2, v112
	v_mov_b32_e32 v13, v197
	v_mov_b32_e32 v41, v117
	v_pk_mul_f32 v[4:5], v[12:13], v[40:41]
	s_nop 0
	v_pk_fma_f32 v[0:1], v[0:1], v[2:3], v[4:5]
	v_mov_b32_e32 v2, v194
	v_mov_b32_e32 v3, v198
	v_mov_b32_e32 v4, v114
	v_mov_b32_e32 v5, v118
	v_pk_fma_f32 v[0:1], v[2:3], v[4:5], v[0:1]
	s_waitcnt vmcnt(21)
	v_mov_b32_e32 v3, v104
	s_waitcnt vmcnt(0)
	v_mov_b32_e32 v5, v132
	s_waitcnt vmcnt(17)
	v_mov_b32_e32 v28, v209
	s_waitcnt vmcnt(2)
	v_mov_b32_e32 v80, v129
	v_mov_b32_e32 v2, v208
	v_mov_b32_e32 v4, v128
	v_mov_b32_e32 v29, v105
	v_mov_b32_e32 v81, v133
	v_pk_mul_f32 v[6:7], v[28:29], v[80:81]
	v_mov_b32_e32 v14, v195
	v_pk_fma_f32 v[2:3], v[2:3], v[4:5], v[6:7]
	v_mov_b32_e32 v4, v210
	v_mov_b32_e32 v5, v106
	v_mov_b32_e32 v6, v130
	v_mov_b32_e32 v7, v134
	v_mov_b32_e32 v42, v115
	v_pk_fma_f32 v[2:3], v[4:5], v[6:7], v[2:3]
	v_mov_b32_e32 v30, v211
	v_mov_b32_e32 v82, v131
	v_mov_b32_e32 v15, v199
	v_mov_b32_e32 v43, v119
	v_pk_fma_f32 v[0:1], v[14:15], v[42:43], v[0:1]
	v_mov_b32_e32 v31, v107
	v_mov_b32_e32 v83, v135
	v_pk_fma_f32 v[2:3], v[30:31], v[82:83], v[2:3]
	s_nop 0
	v_pk_add_f32 v[0:1], v[0:1], v[2:3] neg_lo:[0,1] neg_hi:[0,1]
	v_lshl_add_u64 v[2:3], s[6:7], 0, v[60:61]
	v_add_f32_e32 v0, v16, v0
	global_load_ushort v2, v[2:3], off
	v_add_f32_e32 v0, v0, v1
	s_waitcnt vmcnt(0)
	v_lshlrev_b32_e32 v2, 16, v2
	s_waitcnt vmcnt(2)
	v_fmac_f32_e32 v0, v144, v2
	v_mul_f32_e32 v1, 0x3d372713, v0
	v_mul_f32_e32 v1, v0, v1
	v_fma_f32 v1, v0, v1, v0
	v_mul_f32_e32 v1, 0x3f4c422a, v1
	v_cmp_nlt_f32_e64 s[16:17], |v1|, s42
	s_and_saveexec_b64 s[18:19], s[16:17]
	s_xor_b64 s[16:17], exec, s[18:19]
	s_cbranch_execz .LBB0_1531
	v_add_f32_e64 v2, |v1|, |v1|
	v_mul_f32_e32 v3, 0x3fb8aa3b, v2
	v_rndne_f32_e32 v4, v3
	v_sub_f32_e32 v5, v3, v4
	v_fma_f32 v3, v2, s33, -v3
	v_fmac_f32_e32 v3, 0x32a5705f, v2
	v_add_f32_e32 v3, v5, v3
	v_cvt_i32_f32_e32 v4, v4
	v_exp_f32_e32 v3, v3
	v_cmp_ngt_f32_e32 vcc, s47, v2
	v_ldexp_f32 v3, v3, v4
	s_nop 0
	v_cndmask_b32_e32 v3, 0, v3, vcc
	v_cmp_nlt_f32_e32 vcc, s37, v2
	s_nop 1
	v_cndmask_b32_e32 v2, v220, v3, vcc
	v_add_f32_e32 v2, 1.0, v2
	v_rcp_f32_e32 v2, v2
	s_nop 0
	v_fma_f32 v2, v2, -2.0, 1.0
